# GEMM loops: stage/no-stage test computed once per K-step into vcc, each DMA guard is a single s_cbranch_vccnz (3 fewer scalar ops inside the MFMA segment); placement of later code unchanged
# baseline (speedup 1.0000x reference)
; #define STAGE_ALL(bufi, kt) do { STAGEA(SA(bufi, 0), brow, kt); STAGEA(SA(bufi, 1), brow + HALF, kt); STAGEB(SB(bufi), bcol, kt); } while (0)
; #define WAIT_V(n) asm volatile("s_waitcnt vmcnt(" #n ")" ::: "memory")
; #define BAR __builtin_amdgcn_s_barrier()
;     ...
;   const int wid = tid >> 6, lane = tid & 63, wr = wid >> 1, wc = wid & 1, fr = lane & 15, fq = lane >> 4;
;   acc_t acc;
; #pragma unroll
;   for (int m = 0; m < 4; ++m)
; #pragma unroll
;     for (int n = 0; n < 4; ++n) acc[m][n] = f32x4{0.f, 0.f, 0.f, 0.f};
;   const int nt = K / BK;
;   unsigned oA0, oA1, oB0, oB1;
;   { int _r, _c; stage_rc(tid * 16, _r, _c); oA0 = _r * lda + _c; oB0 = _r * ldb + _c;
;     stage_rc(tid * 16 + 8192, _r, _c); oA1 = _r * lda + _c; oB1 = _r * ldb + _c; }
;   if (!preloaded) {
;     STAGE_ALL(0, 0);
;     if (nt > 1) STAGE_ALL(1, 1);
;   }
;     ...
;     for (int t = 0; t < nt; ++t) {
;       const char* pa = (const char*)SA(b, wr >> 1);
;       const char* pb = (const char*)SB(b);
;       bf16x8 At[4][2], Bf[4][2];
; #pragma unroll
;       for (int m = 0; m < 4; ++m)
; #pragma unroll
;         for (int k = 0; k < 2; ++k) At[m][k] = *reinterpret_cast<const bf16x8*>(pa + lds_byte((wr & 1) * 64 + m * 16 + fr, k * 32 + fq * 8));
; #pragma unroll
;       for (int n = 0; n < 4; ++n)
; #pragma unroll
;         for (int k = 0; k < 2; ++k) Bf[n][k] = *reinterpret_cast<const bf16x8*>(pb + lds_byte(wc * 64 + n * 16 + fr, k * 32 + fq * 8));
;       if (t + 2 < nt) { const int b2 = (b == 0) ? 2 : b - 1; STAGE_ALL(b2, t + 2); WAIT_V(6); } else { WAIT_V(0); }
;       asm volatile("s_waitcnt lgkmcnt(0)" ::: "memory");
;       __builtin_amdgcn_sched_barrier(0);
;       BAR;
.LBB0_40:
	s_or_b64 exec, exec, s[10:11]
	v_and_b32_e32 v8, 15, v133
	v_and_b32_e32 v9, 48, v133
	v_lshl_or_b32 v8, v8, 6, v9
	v_lshlrev_b32_e32 v9, 2, v133
	v_and_b32_e32 v9, 32, v9
	v_xad_u32 v8, v8, v9, 16
	v_lshlrev_b32_e32 v9, 6, v133
	v_lshlrev_b32_e32 v10, 7, v133
	v_and_b32_e32 v9, 0x2000, v9
	v_and_b32_e32 v10, 0x2000, v10
	v_add_u32_e32 v129, v8, v9
	v_add_u32_e32 v131, v8, v10
	v_lshrrev_b32_e32 v8, 1, v4
	v_mul_lo_u32 v4, v6, s66
	s_mov_b32 s61, 0xb000
	v_mad_u64_u32 v[8:9], s[10:11], v8, s61, v[4:5]
	v_or_b32_e32 v4, v8, v5
	s_add_u32 s10, s47, s41
	v_lshrrev_b32_e32 v6, 1, v0
	v_mul_lo_u32 v0, v2, s66
	v_add_u32_sdwa v196, v4, sext(v7) dst_sel:DWORD dst_unused:UNUSED_PAD src0_sel:DWORD src1_sel:WORD_0
	s_addc_u32 s11, s48, s40
	v_mad_u64_u32 v[6:7], s[40:41], v6, s61, v[0:1]
	v_or_b32_e32 v0, v6, v1
	v_lshlrev_b64 v[4:5], 1, v[196:197]
	v_add_u32_sdwa v196, v0, sext(v3) dst_sel:DWORD dst_unused:UNUSED_PAD src0_sel:DWORD src1_sel:WORD_0
	v_lshlrev_b64 v[0:1], 1, v[196:197]
	v_lshl_add_u64 v[134:135], s[10:11], 0, v[4:5]
	v_lshl_add_u64 v[136:137], s[10:11], 0, v[0:1]
	s_add_u32 s10, s54, s37
	s_addc_u32 s11, s55, s36
	v_mov_b32_e32 v60, 0
	v_ashrrev_i32_e32 v132, 8, v133
	v_lshl_add_u64 v[138:139], s[10:11], 0, v[4:5]
	v_lshl_add_u64 v[140:141], s[10:11], 0, v[0:1]
	s_mov_b32 s61, 0
	s_mov_b64 s[10:11], 0
	s_mov_b32 s62, 0
	v_mov_b32_e32 v61, v60
	v_mov_b32_e32 v62, v60
	v_mov_b32_e32 v63, v60
	v_mov_b32_e32 v56, v60
	v_mov_b32_e32 v57, v60
	v_mov_b32_e32 v58, v60
	v_mov_b32_e32 v59, v60
	v_mov_b32_e32 v52, v60
	v_mov_b32_e32 v53, v60
	v_mov_b32_e32 v54, v60
	v_mov_b32_e32 v55, v60
	v_mov_b32_e32 v48, v60
	v_mov_b32_e32 v49, v60
	v_mov_b32_e32 v50, v60
	v_mov_b32_e32 v51, v60
	v_mov_b32_e32 v44, v60
	v_mov_b32_e32 v45, v60
	v_mov_b32_e32 v46, v60
	v_mov_b32_e32 v47, v60
	v_mov_b32_e32 v40, v60
	v_mov_b32_e32 v41, v60
	v_mov_b32_e32 v42, v60
	v_mov_b32_e32 v43, v60
	v_mov_b32_e32 v36, v60
	v_mov_b32_e32 v37, v60
	v_mov_b32_e32 v38, v60
	v_mov_b32_e32 v39, v60
	v_mov_b32_e32 v32, v60
	v_mov_b32_e32 v33, v60
	v_mov_b32_e32 v34, v60
	v_mov_b32_e32 v35, v60
	v_mov_b32_e32 v28, v60
	v_mov_b32_e32 v29, v60
	v_mov_b32_e32 v30, v60
	v_mov_b32_e32 v31, v60
	v_mov_b32_e32 v24, v60
	v_mov_b32_e32 v25, v60
	v_mov_b32_e32 v26, v60
	v_mov_b32_e32 v27, v60
	v_mov_b32_e32 v20, v60
	v_mov_b32_e32 v21, v60
	v_mov_b32_e32 v22, v60
	v_mov_b32_e32 v23, v60
	v_mov_b32_e32 v16, v60
	v_mov_b32_e32 v17, v60
	v_mov_b32_e32 v18, v60
	v_mov_b32_e32 v19, v60
	v_mov_b32_e32 v12, v60
	v_mov_b32_e32 v13, v60
	v_mov_b32_e32 v14, v60
	v_mov_b32_e32 v15, v60
	v_mov_b32_e32 v8, v60
	v_mov_b32_e32 v9, v60
	v_mov_b32_e32 v10, v60
	v_mov_b32_e32 v11, v60
	v_mov_b32_e32 v4, v60
	v_mov_b32_e32 v5, v60
	v_mov_b32_e32 v6, v60
	v_mov_b32_e32 v7, v60
	v_mov_b32_e32 v0, v60
	v_mov_b32_e32 v1, v60
	v_mov_b32_e32 v2, v60
	v_mov_b32_e32 v3, v60
	v_readfirstlane_b32 s99, v151
	v_lshl_add_u32 v174, v132, 14, v129
	v_mov_b32_e32 v161, v131
	v_lshl_add_u64 v[162:163], v[140:141], 0, s[16:17]
	v_lshl_add_u64 v[164:165], v[138:139], 0, s[16:17]
	v_lshl_add_u64 v[166:167], v[140:141], 0, s[18:19]
	v_lshl_add_u64 v[168:169], v[138:139], 0, s[18:19]
	v_mov_b64_e32 v[170:171], v[136:137]
	v_mov_b64_e32 v[172:173], v[134:135]
	v_mov_b32_e32 v160, v174
	s_add_u32 s98, s99, 0x18000
	s_mov_b64 vcc, 0
.LBB0_42:
	ds_read_b128 v[108:111], v160
	ds_read_b128 v[76:79], v160 offset:1024
	ds_read_b128 v[104:107], v160 offset:2048
	ds_read_b128 v[72:75], v160 offset:3072
	ds_read_b128 v[100:103], v160 offset:4096
	ds_read_b128 v[68:71], v160 offset:5120
	ds_read_b128 v[96:99], v160 offset:6144
	ds_read_b128 v[64:67], v160 offset:7168
	ds_read_b128 v[112:115], v161 offset:32768
	ds_read_b128 v[80:83], v161 offset:33792
	ds_read_b128 v[116:119], v161 offset:34816
	ds_read_b128 v[84:87], v161 offset:35840
	ds_read_b128 v[120:123], v161 offset:36864
	ds_read_b128 v[88:91], v161 offset:37888
	ds_read_b128 v[124:127], v161 offset:38912
	ds_read_b128 v[92:95], v161 offset:39936
	s_cbranch_vccnz .Lgc1_nostage
	s_mov_b32 m0, s98
	s_nop 0
	global_load_lds_dwordx4 v[162:163], off
	s_add_u32 m0, s98, 0x2000
	s_nop 0
	global_load_lds_dwordx4 v[164:165], off
	s_add_u32 m0, s98, 0x4000
	s_nop 0
	global_load_lds_dwordx4 v[166:167], off
	s_waitcnt vmcnt(3)
; #define STAGE_ALL(bufi, kt) do { STAGEA(SA(bufi, 0), brow, kt); STAGEA(SA(bufi, 1), brow + HALF, kt); STAGEB(SB(bufi), bcol, kt); } while (0)
; #define WAIT_V(n) asm volatile("s_waitcnt vmcnt(" #n ")" ::: "memory")
; #define BAR __builtin_amdgcn_s_barrier()
;     ...
;       if (t + 2 < nt) { const int b2 = (b == 0) ? 2 : b - 1; STAGE_ALL(b2, t + 2); WAIT_V(6); } else { WAIT_V(0); }
;       asm volatile("s_waitcnt lgkmcnt(0)" ::: "memory");
;       __builtin_amdgcn_sched_barrier(0);
;       BAR;
;       __builtin_amdgcn_sched_barrier(0);
;       __builtin_amdgcn_s_setprio(1);
; #pragma unroll
;       for (int k = 0; k < 2; ++k)
; #pragma unroll
;         for (int m = 0; m < 4; ++m)
; #pragma unroll
;           for (int n = 0; n < 4; ++n) acc[m][n] = __builtin_amdgcn_mfma_f32_16x16x32_bf16(Bf[n][k], At[m][k], acc[m][n], 0, 0, 0);
;       __builtin_amdgcn_s_setprio(0);
;       __builtin_amdgcn_sched_barrier(0);
;       BAR;
;       __builtin_amdgcn_sched_barrier(0);
;       b = (b == 2) ? 0 : b + 1;
.LBB0_41:
	s_waitcnt lgkmcnt(0)
	s_barrier
	s_setprio 1
	s_waitcnt lgkmcnt(0)
	v_mfma_f32_16x16x32_bf16 v[60:63], v[112:115], v[108:111], v[60:63]
	v_mfma_f32_16x16x32_bf16 v[56:59], v[116:119], v[108:111], v[56:59]
	s_cbranch_vccnz .Lgc1_skd3
	s_add_u32 m0, s98, 0x6000
	s_nop 0
	global_load_lds_dwordx4 v[168:169], off
.Lgc1_skd3:
	v_mfma_f32_16x16x32_bf16 v[52:55], v[120:123], v[108:111], v[52:55]
	v_mfma_f32_16x16x32_bf16 v[48:51], v[124:127], v[108:111], v[48:51]
	v_mfma_f32_16x16x32_bf16 v[44:47], v[112:115], v[104:107], v[44:47]
	v_mfma_f32_16x16x32_bf16 v[40:43], v[116:119], v[104:107], v[40:43]
	s_cbranch_vccnz .Lgc1_skd4
	s_add_u32 m0, s98, 0x8000
	s_nop 0
	global_load_lds_dwordx4 v[170:171], off
.Lgc1_skd4:
	v_mfma_f32_16x16x32_bf16 v[36:39], v[120:123], v[104:107], v[36:39]
	v_mfma_f32_16x16x32_bf16 v[32:35], v[124:127], v[104:107], v[32:35]
	v_mfma_f32_16x16x32_bf16 v[28:31], v[112:115], v[100:103], v[28:31]
	v_mfma_f32_16x16x32_bf16 v[24:27], v[116:119], v[100:103], v[24:27]
	s_cbranch_vccnz .Lgc1_skd5
	s_add_u32 m0, s98, 0xa000
	s_nop 0
	global_load_lds_dwordx4 v[172:173], off
.Lgc1_skd5:
	v_mfma_f32_16x16x32_bf16 v[20:23], v[120:123], v[100:103], v[20:23]
	v_mfma_f32_16x16x32_bf16 v[16:19], v[124:127], v[100:103], v[16:19]
	v_mfma_f32_16x16x32_bf16 v[12:15], v[112:115], v[96:99], v[12:15]
	s_add_i32 s36, s61, 1
	s_cmp_lg_u32 s61, 2
	s_cselect_b32 s61, s36, 0
	s_add_i32 s62, s62, 1
	s_cmp_gt_u32 s62, 41
	s_cselect_b64 vcc, -1, 0
	s_add_u32 s10, s10, 0x80
	s_addc_u32 s11, s11, 0
	s_mul_i32 s36, s61, 0xc000
	s_mul_i32 s98, s61, 0x6000
	s_addk_i32 s98, 0xa000
	s_cmp_lg_u32 s61, 0
	s_cselect_b32 s98, s98, 0xc000
	s_lshl_b32 s98, s98, 1
	s_add_u32 s98, s98, s99
	v_mfma_f32_16x16x32_bf16 v[8:11], v[116:119], v[96:99], v[8:11]
	v_mfma_f32_16x16x32_bf16 v[4:7], v[120:123], v[96:99], v[4:7]
	v_add_u32_e32 v160, s36, v174
	v_mfma_f32_16x16x32_bf16 v[0:3], v[124:127], v[96:99], v[0:3]
	v_mfma_f32_16x16x32_bf16 v[60:63], v[80:83], v[76:79], v[60:63]
	v_add_u32_e32 v161, s36, v131
	v_mfma_f32_16x16x32_bf16 v[56:59], v[84:87], v[76:79], v[56:59]
	v_mfma_f32_16x16x32_bf16 v[52:55], v[88:91], v[76:79], v[52:55]
	v_lshl_add_u64 v[162:163], v[162:163], 0, s[14:15]
	v_mfma_f32_16x16x32_bf16 v[48:51], v[92:95], v[76:79], v[48:51]
	v_mfma_f32_16x16x32_bf16 v[44:47], v[80:83], v[72:75], v[44:47]
	v_lshl_add_u64 v[164:165], v[164:165], 0, s[14:15]
	v_mfma_f32_16x16x32_bf16 v[40:43], v[84:87], v[72:75], v[40:43]
	v_mfma_f32_16x16x32_bf16 v[36:39], v[88:91], v[72:75], v[36:39]
	v_lshl_add_u64 v[166:167], v[166:167], 0, s[14:15]
	v_mfma_f32_16x16x32_bf16 v[32:35], v[92:95], v[72:75], v[32:35]
	v_mfma_f32_16x16x32_bf16 v[28:31], v[80:83], v[68:71], v[28:31]
	v_lshl_add_u64 v[168:169], v[168:169], 0, s[14:15]
	v_mfma_f32_16x16x32_bf16 v[24:27], v[84:87], v[68:71], v[24:27]
	v_mfma_f32_16x16x32_bf16 v[20:23], v[88:91], v[68:71], v[20:23]
	v_lshl_add_u64 v[170:171], v[170:171], 0, s[14:15]
	v_mfma_f32_16x16x32_bf16 v[16:19], v[92:95], v[68:71], v[16:19]
	v_mfma_f32_16x16x32_bf16 v[12:15], v[80:83], v[64:67], v[12:15]
	v_lshl_add_u64 v[172:173], v[172:173], 0, s[14:15]
	v_mfma_f32_16x16x32_bf16 v[8:11], v[84:87], v[64:67], v[8:11]
	v_mfma_f32_16x16x32_bf16 v[4:7], v[88:91], v[64:67], v[4:7]
	v_mfma_f32_16x16x32_bf16 v[0:3], v[92:95], v[64:67], v[0:3]
	s_setprio 0
	s_barrier
	s_cmpk_eq_i32 s10, 0x1600
	s_cbranch_scc0 .LBB0_42
	s_branch .LBB0_46
.Lgc1_nostage:
	s_waitcnt vmcnt(0)
	s_branch .LBB0_41
	s_nop 0
	s_nop 0

; #define STAGE_ALL(bufi, kt) do { STAGEA(SA(bufi, 0), brow, kt); STAGEA(SA(bufi, 1), brow + HALF, kt); STAGEB(SB(bufi), bcol, kt); } while (0)
;     ...
;   const int wid = tid >> 6, lane = tid & 63, wr = wid >> 1, wc = wid & 1, fr = lane & 15, fq = lane >> 4;
;   acc_t acc;
; #pragma unroll
;   for (int m = 0; m < 4; ++m)
; #pragma unroll
;     for (int n = 0; n < 4; ++n) acc[m][n] = f32x4{0.f, 0.f, 0.f, 0.f};
;   const int nt = K / BK;
;   unsigned oA0, oA1, oB0, oB1;
;   { int _r, _c; stage_rc(tid * 16, _r, _c); oA0 = _r * lda + _c; oB0 = _r * ldb + _c;
;     stage_rc(tid * 16 + 8192, _r, _c); oA1 = _r * lda + _c; oB1 = _r * ldb + _c; }
;   if (!preloaded) {
;     STAGE_ALL(0, 0);
;     if (nt > 1) STAGE_ALL(1, 1);
;   }
.LBB0_72:
	s_or_b64 exec, exec, s[44:45]
	v_lshlrev_b32_e32 v4, 13, v4
	v_and_b32_e32 v4, 0xffffc000, v4
	v_lshlrev_b32_e32 v0, 13, v0
	v_lshl_add_u32 v4, v5, 10, v4
	v_and_b32_e32 v0, 0xffffc000, v0
	s_ashr_i32 s43, s42, 31
	s_ashr_i32 s11, s10, 31
	v_or_b32_e32 v4, v4, v6
	v_lshl_add_u32 v0, v1, 10, v0
	v_and_b32_e32 v8, 15, v133
	v_and_b32_e32 v9, 48, v133
	s_lshl_b64 s[36:37], s[42:43], 11
	s_lshl_b64 s[10:11], s[10:11], 11
	v_add_u32_sdwa v196, v4, sext(v7) dst_sel:DWORD dst_unused:UNUSED_PAD src0_sel:DWORD src1_sel:WORD_0
	v_or_b32_e32 v0, v0, v2
	v_lshl_or_b32 v8, v8, 6, v9
	v_lshlrev_b32_e32 v9, 2, v133
	v_lshlrev_b64 v[4:5], 1, v[196:197]
	s_add_u32 s10, s51, s10
	v_add_u32_sdwa v196, v0, sext(v3) dst_sel:DWORD dst_unused:UNUSED_PAD src0_sel:DWORD src1_sel:WORD_0
	v_and_b32_e32 v9, 32, v9
	s_addc_u32 s11, s58, s11
	v_lshlrev_b64 v[0:1], 1, v[196:197]
	v_xad_u32 v8, v8, v9, 16
	v_lshlrev_b32_e32 v9, 6, v133
	v_lshlrev_b32_e32 v10, 7, v133
	v_lshl_add_u64 v[134:135], s[10:11], 0, v[4:5]
	v_lshl_add_u64 v[136:137], s[10:11], 0, v[0:1]
	s_add_u32 s10, s54, s36
	v_and_b32_e32 v9, 0x2000, v9
	v_and_b32_e32 v10, 0x2000, v10
	s_addc_u32 s11, s55, s37
	v_mov_b32_e32 v56, 0
	v_ashrrev_i32_e32 v132, 8, v133
	v_add_u32_e32 v129, v8, v9
	v_add_u32_e32 v131, v8, v10
	v_lshl_add_u64 v[138:139], s[10:11], 0, v[4:5]
	v_lshl_add_u64 v[140:141], s[10:11], 0, v[0:1]
	s_mov_b32 s43, 0
	s_mov_b64 s[10:11], 0
	s_mov_b32 s64, 0
	v_mov_b32_e32 v57, v56
	v_mov_b32_e32 v58, v56
	v_mov_b32_e32 v59, v56
	v_mov_b32_e32 v48, v56
	v_mov_b32_e32 v49, v56
	v_mov_b32_e32 v50, v56
	v_mov_b32_e32 v51, v56
	v_mov_b32_e32 v60, v56
	v_mov_b32_e32 v61, v56
	v_mov_b32_e32 v62, v56
	v_mov_b32_e32 v63, v56
	v_mov_b32_e32 v52, v56
	v_mov_b32_e32 v53, v56
	v_mov_b32_e32 v54, v56
	v_mov_b32_e32 v55, v56
	v_mov_b32_e32 v40, v56
	v_mov_b32_e32 v41, v56
	v_mov_b32_e32 v42, v56
	v_mov_b32_e32 v43, v56
	v_mov_b32_e32 v32, v56
	v_mov_b32_e32 v33, v56
	v_mov_b32_e32 v34, v56
	v_mov_b32_e32 v35, v56
	v_mov_b32_e32 v44, v56
	v_mov_b32_e32 v45, v56
	v_mov_b32_e32 v46, v56
	v_mov_b32_e32 v47, v56
	v_mov_b32_e32 v36, v56
	v_mov_b32_e32 v37, v56
	v_mov_b32_e32 v38, v56
	v_mov_b32_e32 v39, v56
	v_mov_b32_e32 v24, v56
	v_mov_b32_e32 v25, v56
	v_mov_b32_e32 v26, v56
	v_mov_b32_e32 v27, v56
	v_mov_b32_e32 v16, v56
	v_mov_b32_e32 v17, v56
	v_mov_b32_e32 v18, v56
	v_mov_b32_e32 v19, v56
	v_mov_b32_e32 v28, v56
	v_mov_b32_e32 v29, v56
	v_mov_b32_e32 v30, v56
	v_mov_b32_e32 v31, v56
	v_mov_b32_e32 v20, v56
	v_mov_b32_e32 v21, v56
	v_mov_b32_e32 v22, v56
	v_mov_b32_e32 v23, v56
	v_mov_b32_e32 v8, v56
	v_mov_b32_e32 v9, v56
	v_mov_b32_e32 v10, v56
	v_mov_b32_e32 v11, v56
	v_mov_b32_e32 v0, v56
	v_mov_b32_e32 v1, v56
	v_mov_b32_e32 v2, v56
	v_mov_b32_e32 v3, v56
	v_mov_b32_e32 v12, v56
	v_mov_b32_e32 v13, v56
	v_mov_b32_e32 v14, v56
	v_mov_b32_e32 v15, v56
	v_mov_b32_e32 v4, v56
	v_mov_b32_e32 v5, v56
	v_mov_b32_e32 v6, v56
	v_mov_b32_e32 v7, v56
	v_readfirstlane_b32 s99, v151
	v_lshl_add_u32 v174, v132, 14, v129
	v_mov_b32_e32 v161, v131
	v_lshl_add_u64 v[162:163], v[140:141], 0, s[20:21]
	v_lshl_add_u64 v[164:165], v[138:139], 0, s[20:21]
	v_lshl_add_u64 v[166:167], v[140:141], 0, s[22:23]
	v_lshl_add_u64 v[168:169], v[138:139], 0, s[22:23]
	v_mov_b64_e32 v[170:171], v[136:137]
	v_mov_b64_e32 v[172:173], v[134:135]
	v_mov_b32_e32 v160, v174
	s_add_u32 s98, s99, 0x18000
	s_mov_b64 vcc, 0

; #define STAGE_ALL(bufi, kt) do { STAGEA(SA(bufi, 0), brow, kt); STAGEA(SA(bufi, 1), brow + HALF, kt); STAGEB(SB(bufi), bcol, kt); } while (0)
; #define WAIT_V(n) asm volatile("s_waitcnt vmcnt(" #n ")" ::: "memory")
; #define BAR __builtin_amdgcn_s_barrier()
;     ...
;       if (t + 2 < nt) { const int b2 = (b == 0) ? 2 : b - 1; STAGE_ALL(b2, t + 2); WAIT_V(6); } else { WAIT_V(0); }
;       asm volatile("s_waitcnt lgkmcnt(0)" ::: "memory");
;       __builtin_amdgcn_sched_barrier(0);
;       BAR;
;       __builtin_amdgcn_sched_barrier(0);
;       __builtin_amdgcn_s_setprio(1);
; #pragma unroll
;       for (int k = 0; k < 2; ++k)
; #pragma unroll
;         for (int m = 0; m < 4; ++m)
; #pragma unroll
;           for (int n = 0; n < 4; ++n) acc[m][n] = __builtin_amdgcn_mfma_f32_16x16x32_bf16(Bf[n][k], At[m][k], acc[m][n], 0, 0, 0);
;       __builtin_amdgcn_s_setprio(0);
;       __builtin_amdgcn_sched_barrier(0);
;       BAR;
;       __builtin_amdgcn_sched_barrier(0);
;       b = (b == 2) ? 0 : b + 1;
.LBB0_73:
	s_waitcnt lgkmcnt(0)
	s_barrier
	s_setprio 1
	s_waitcnt lgkmcnt(0)
	v_mfma_f32_16x16x32_bf16 v[56:59], v[112:115], v[108:111], v[56:59]
	v_mfma_f32_16x16x32_bf16 v[48:51], v[116:119], v[108:111], v[48:51]
	s_cbranch_vccnz .Lgc2_skd3
	s_add_u32 m0, s98, 0x6000
	s_nop 0
	global_load_lds_dwordx4 v[168:169], off
.Lgc2_skd3:
	v_mfma_f32_16x16x32_bf16 v[60:63], v[120:123], v[108:111], v[60:63]
	v_mfma_f32_16x16x32_bf16 v[52:55], v[124:127], v[108:111], v[52:55]
	v_mfma_f32_16x16x32_bf16 v[40:43], v[112:115], v[104:107], v[40:43]
	v_mfma_f32_16x16x32_bf16 v[32:35], v[116:119], v[104:107], v[32:35]
	s_cbranch_vccnz .Lgc2_skd4
	s_add_u32 m0, s98, 0x8000
	s_nop 0
	global_load_lds_dwordx4 v[170:171], off
.Lgc2_skd4:
	v_mfma_f32_16x16x32_bf16 v[44:47], v[120:123], v[104:107], v[44:47]
	v_mfma_f32_16x16x32_bf16 v[36:39], v[124:127], v[104:107], v[36:39]
	v_mfma_f32_16x16x32_bf16 v[24:27], v[112:115], v[100:103], v[24:27]
	v_mfma_f32_16x16x32_bf16 v[16:19], v[116:119], v[100:103], v[16:19]
	s_cbranch_vccnz .Lgc2_skd5
	s_add_u32 m0, s98, 0xa000
	s_nop 0
	global_load_lds_dwordx4 v[172:173], off
.Lgc2_skd5:
	v_mfma_f32_16x16x32_bf16 v[28:31], v[120:123], v[100:103], v[28:31]
	v_mfma_f32_16x16x32_bf16 v[20:23], v[124:127], v[100:103], v[20:23]
	v_mfma_f32_16x16x32_bf16 v[8:11], v[112:115], v[96:99], v[8:11]
	s_add_i32 s36, s43, 1
	s_cmp_lg_u32 s43, 2
	s_cselect_b32 s43, s36, 0
	s_add_i32 s64, s64, 1
	s_cmp_gt_u32 s64, 13
	s_cselect_b64 vcc, -1, 0
	s_add_u32 s10, s10, 0x80
	s_addc_u32 s11, s11, 0
	s_mul_i32 s36, s43, 0xc000
	s_mul_i32 s98, s43, 0x6000
	s_addk_i32 s98, 0xa000
	s_cmp_lg_u32 s43, 0
	s_cselect_b32 s98, s98, 0xc000
	s_lshl_b32 s98, s98, 1
	s_add_u32 s98, s98, s99
	v_mfma_f32_16x16x32_bf16 v[0:3], v[116:119], v[96:99], v[0:3]
	v_mfma_f32_16x16x32_bf16 v[12:15], v[120:123], v[96:99], v[12:15]
	v_add_u32_e32 v160, s36, v174
	v_mfma_f32_16x16x32_bf16 v[4:7], v[124:127], v[96:99], v[4:7]
	v_mfma_f32_16x16x32_bf16 v[56:59], v[80:83], v[76:79], v[56:59]
	v_add_u32_e32 v161, s36, v131
	v_mfma_f32_16x16x32_bf16 v[48:51], v[84:87], v[76:79], v[48:51]
	v_mfma_f32_16x16x32_bf16 v[60:63], v[88:91], v[76:79], v[60:63]
	v_lshl_add_u64 v[162:163], v[162:163], 0, s[14:15]
	v_mfma_f32_16x16x32_bf16 v[52:55], v[92:95], v[76:79], v[52:55]
	v_mfma_f32_16x16x32_bf16 v[40:43], v[80:83], v[72:75], v[40:43]
	v_lshl_add_u64 v[164:165], v[164:165], 0, s[14:15]
	v_mfma_f32_16x16x32_bf16 v[32:35], v[84:87], v[72:75], v[32:35]
	v_mfma_f32_16x16x32_bf16 v[44:47], v[88:91], v[72:75], v[44:47]
	v_lshl_add_u64 v[166:167], v[166:167], 0, s[14:15]
	v_mfma_f32_16x16x32_bf16 v[36:39], v[92:95], v[72:75], v[36:39]
	v_mfma_f32_16x16x32_bf16 v[24:27], v[80:83], v[68:71], v[24:27]
	v_lshl_add_u64 v[168:169], v[168:169], 0, s[14:15]
	v_mfma_f32_16x16x32_bf16 v[16:19], v[84:87], v[68:71], v[16:19]
	v_mfma_f32_16x16x32_bf16 v[28:31], v[88:91], v[68:71], v[28:31]
	v_lshl_add_u64 v[170:171], v[170:171], 0, s[14:15]
	v_mfma_f32_16x16x32_bf16 v[20:23], v[92:95], v[68:71], v[20:23]
	v_mfma_f32_16x16x32_bf16 v[8:11], v[80:83], v[64:67], v[8:11]
	v_lshl_add_u64 v[172:173], v[172:173], 0, s[14:15]
	v_mfma_f32_16x16x32_bf16 v[0:3], v[84:87], v[64:67], v[0:3]
	v_mfma_f32_16x16x32_bf16 v[12:15], v[88:91], v[64:67], v[12:15]
	v_mfma_f32_16x16x32_bf16 v[4:7], v[92:95], v[64:67], v[4:7]
	s_setprio 0
	s_barrier
	s_cmpk_eq_i32 s10, 0x800
	s_cbranch_scc0 .LBB0_74
	s_branch .LBB0_78

; #define STAGE_ALL(bufi, kt) do { STAGEA(SA(bufi, 0), brow, kt); STAGEA(SA(bufi, 1), brow + HALF, kt); STAGEB(SB(bufi), bcol, kt); } while (0)
;     ...
;   const int wid = tid >> 6, lane = tid & 63, wr = wid >> 1, wc = wid & 1, fr = lane & 15, fq = lane >> 4;
;   acc_t acc;
; #pragma unroll
;   for (int m = 0; m < 4; ++m)
; #pragma unroll
;     for (int n = 0; n < 4; ++n) acc[m][n] = f32x4{0.f, 0.f, 0.f, 0.f};
;   const int nt = K / BK;
;   unsigned oA0, oA1, oB0, oB1;
;   { int _r, _c; stage_rc(tid * 16, _r, _c); oA0 = _r * lda + _c; oB0 = _r * ldb + _c;
;     stage_rc(tid * 16 + 8192, _r, _c); oA1 = _r * lda + _c; oB1 = _r * ldb + _c; }
;   if (!preloaded) {
;     STAGE_ALL(0, 0);
;     if (nt > 1) STAGE_ALL(1, 1);
;   }
.LBB0_107:
	s_or_b64 exec, exec, s[10:11]
	v_lshlrev_b32_e32 v4, 13, v4
	s_ashr_i32 s41, s40, 31
	s_ashr_i32 s39, s38, 31
	v_and_b32_e32 v4, 0xffffc000, v4
	v_lshlrev_b32_e32 v0, 13, v0
	v_and_b32_e32 v8, 15, v133
	v_and_b32_e32 v9, 48, v133
	s_lshl_b64 s[10:11], s[40:41], 11
	s_lshl_b64 s[36:37], s[38:39], 11
	v_lshl_add_u32 v4, v5, 10, v4
	v_and_b32_e32 v0, 0xffffc000, v0
	v_lshl_or_b32 v8, v8, 6, v9
	v_lshlrev_b32_e32 v9, 2, v133
	v_or_b32_e32 v4, v4, v6
	s_add_u32 s36, s59, s36
	v_lshl_add_u32 v0, v1, 10, v0
	v_and_b32_e32 v9, 32, v9
	v_add_u32_sdwa v196, v4, sext(v7) dst_sel:DWORD dst_unused:UNUSED_PAD src0_sel:DWORD src1_sel:WORD_0
	s_addc_u32 s37, s60, s37
	v_or_b32_e32 v0, v0, v2
	v_xad_u32 v8, v8, v9, 16
	v_lshlrev_b32_e32 v9, 6, v133
	v_lshlrev_b32_e32 v10, 7, v133
	v_lshlrev_b64 v[4:5], 1, v[196:197]
	v_add_u32_sdwa v196, v0, sext(v3) dst_sel:DWORD dst_unused:UNUSED_PAD src0_sel:DWORD src1_sel:WORD_0
	s_add_u32 s10, s54, s10
	v_and_b32_e32 v9, 0x2000, v9
	v_and_b32_e32 v10, 0x2000, v10
	v_lshlrev_b64 v[0:1], 1, v[196:197]
	s_addc_u32 s11, s55, s11
	v_mov_b32_e32 v60, 0
	v_ashrrev_i32_e32 v132, 8, v133
	v_add_u32_e32 v129, v8, v9
	v_add_u32_e32 v131, v8, v10
	v_lshl_add_u64 v[134:135], s[36:37], 0, v[4:5]
	v_lshl_add_u64 v[136:137], s[36:37], 0, v[0:1]
	v_lshl_add_u64 v[138:139], s[10:11], 0, v[4:5]
	v_lshl_add_u64 v[140:141], s[10:11], 0, v[0:1]
	s_mov_b32 s39, 0
	s_mov_b64 s[10:11], 0
	s_mov_b32 s41, 0
	v_mov_b32_e32 v61, v60
	v_mov_b32_e32 v62, v60
	v_mov_b32_e32 v63, v60
	v_mov_b32_e32 v56, v60
	v_mov_b32_e32 v57, v60
	v_mov_b32_e32 v58, v60
	v_mov_b32_e32 v59, v60
	v_mov_b32_e32 v52, v60
	v_mov_b32_e32 v53, v60
	v_mov_b32_e32 v54, v60
	v_mov_b32_e32 v55, v60
	v_mov_b32_e32 v48, v60
	v_mov_b32_e32 v49, v60
	v_mov_b32_e32 v50, v60
	v_mov_b32_e32 v51, v60
	v_mov_b32_e32 v44, v60
	v_mov_b32_e32 v45, v60
	v_mov_b32_e32 v46, v60
	v_mov_b32_e32 v47, v60
	v_mov_b32_e32 v40, v60
	v_mov_b32_e32 v41, v60
	v_mov_b32_e32 v42, v60
	v_mov_b32_e32 v43, v60
	v_mov_b32_e32 v36, v60
	v_mov_b32_e32 v37, v60
	v_mov_b32_e32 v38, v60
	v_mov_b32_e32 v39, v60
	v_mov_b32_e32 v32, v60
	v_mov_b32_e32 v33, v60
	v_mov_b32_e32 v34, v60
	v_mov_b32_e32 v35, v60
	v_mov_b32_e32 v28, v60
	v_mov_b32_e32 v29, v60
	v_mov_b32_e32 v30, v60
	v_mov_b32_e32 v31, v60
	v_mov_b32_e32 v24, v60
	v_mov_b32_e32 v25, v60
	v_mov_b32_e32 v26, v60
	v_mov_b32_e32 v27, v60
	v_mov_b32_e32 v20, v60
	v_mov_b32_e32 v21, v60
	v_mov_b32_e32 v22, v60
	v_mov_b32_e32 v23, v60
	v_mov_b32_e32 v16, v60
	v_mov_b32_e32 v17, v60
	v_mov_b32_e32 v18, v60
	v_mov_b32_e32 v19, v60
	v_mov_b32_e32 v12, v60
	v_mov_b32_e32 v13, v60
	v_mov_b32_e32 v14, v60
	v_mov_b32_e32 v15, v60
	v_mov_b32_e32 v8, v60
	v_mov_b32_e32 v9, v60
	v_mov_b32_e32 v10, v60
	v_mov_b32_e32 v11, v60
	v_mov_b32_e32 v4, v60
	v_mov_b32_e32 v5, v60
	v_mov_b32_e32 v6, v60
	v_mov_b32_e32 v7, v60
	v_mov_b32_e32 v0, v60
	v_mov_b32_e32 v1, v60
	v_mov_b32_e32 v2, v60
	v_mov_b32_e32 v3, v60
	v_readfirstlane_b32 s99, v151
	v_lshl_add_u32 v174, v132, 14, v129
	v_mov_b32_e32 v161, v131
	v_lshl_add_u64 v[162:163], v[140:141], 0, s[24:25]
	v_lshl_add_u64 v[164:165], v[138:139], 0, s[24:25]
	v_lshl_add_u64 v[166:167], v[140:141], 0, s[26:27]
	v_lshl_add_u64 v[168:169], v[138:139], 0, s[26:27]
	v_mov_b64_e32 v[170:171], v[136:137]
	v_mov_b64_e32 v[172:173], v[134:135]
	v_mov_b32_e32 v160, v174
	s_add_u32 s98, s99, 0x18000
	s_mov_b64 vcc, 0

; #define BAR __builtin_amdgcn_s_barrier()
;     ...
; #pragma unroll
;       for (int k = 0; k < 2; ++k)
; #pragma unroll
;         for (int m = 0; m < 4; ++m)
; #pragma unroll
;           for (int n = 0; n < 4; ++n) acc[m][n] = __builtin_amdgcn_mfma_f32_16x16x32_bf16(Bf[n][k], At[m][k], acc[m][n], 0, 0, 0);
;       __builtin_amdgcn_s_setprio(0);
;       __builtin_amdgcn_sched_barrier(0);
;       BAR;
;       __builtin_amdgcn_sched_barrier(0);
;       b = (b == 2) ? 0 : b + 1;
.Lgc3_skd5:
	v_mfma_f32_16x16x32_bf16 v[20:23], v[120:123], v[100:103], v[20:23]
	v_mfma_f32_16x16x32_bf16 v[16:19], v[124:127], v[100:103], v[16:19]
	v_mfma_f32_16x16x32_bf16 v[12:15], v[112:115], v[96:99], v[12:15]
	s_add_i32 s36, s39, 1
	s_cmp_lg_u32 s39, 2
	s_cselect_b32 s39, s36, 0
	s_add_i32 s41, s41, 1
	s_cmp_gt_u32 s41, 13
	s_cselect_b64 vcc, -1, 0
	s_add_u32 s10, s10, 0x80
	s_addc_u32 s11, s11, 0
	s_mul_i32 s36, s39, 0xc000
	s_mul_i32 s98, s39, 0x6000
	s_addk_i32 s98, 0xa000
	s_cmp_lg_u32 s39, 0
	s_cselect_b32 s98, s98, 0xc000
	s_lshl_b32 s98, s98, 1
	s_add_u32 s98, s98, s99
	v_mfma_f32_16x16x32_bf16 v[8:11], v[116:119], v[96:99], v[8:11]
	v_mfma_f32_16x16x32_bf16 v[4:7], v[120:123], v[96:99], v[4:7]
	v_add_u32_e32 v160, s36, v174
	v_mfma_f32_16x16x32_bf16 v[0:3], v[124:127], v[96:99], v[0:3]
	v_mfma_f32_16x16x32_bf16 v[60:63], v[80:83], v[76:79], v[60:63]
	v_add_u32_e32 v161, s36, v131
	v_mfma_f32_16x16x32_bf16 v[56:59], v[84:87], v[76:79], v[56:59]
	v_mfma_f32_16x16x32_bf16 v[52:55], v[88:91], v[76:79], v[52:55]
	v_lshl_add_u64 v[162:163], v[162:163], 0, s[14:15]
	v_mfma_f32_16x16x32_bf16 v[48:51], v[92:95], v[76:79], v[48:51]
	v_mfma_f32_16x16x32_bf16 v[44:47], v[80:83], v[72:75], v[44:47]
	v_lshl_add_u64 v[164:165], v[164:165], 0, s[14:15]
	v_mfma_f32_16x16x32_bf16 v[40:43], v[84:87], v[72:75], v[40:43]
	v_mfma_f32_16x16x32_bf16 v[36:39], v[88:91], v[72:75], v[36:39]
	v_lshl_add_u64 v[166:167], v[166:167], 0, s[14:15]
	v_mfma_f32_16x16x32_bf16 v[32:35], v[92:95], v[72:75], v[32:35]
	v_mfma_f32_16x16x32_bf16 v[28:31], v[80:83], v[68:71], v[28:31]
	v_lshl_add_u64 v[168:169], v[168:169], 0, s[14:15]
	v_mfma_f32_16x16x32_bf16 v[24:27], v[84:87], v[68:71], v[24:27]
	v_mfma_f32_16x16x32_bf16 v[20:23], v[88:91], v[68:71], v[20:23]
	v_lshl_add_u64 v[170:171], v[170:171], 0, s[14:15]
	v_mfma_f32_16x16x32_bf16 v[16:19], v[92:95], v[68:71], v[16:19]
	v_mfma_f32_16x16x32_bf16 v[12:15], v[80:83], v[64:67], v[12:15]
	v_lshl_add_u64 v[172:173], v[172:173], 0, s[14:15]
	v_mfma_f32_16x16x32_bf16 v[8:11], v[84:87], v[64:67], v[8:11]
	v_mfma_f32_16x16x32_bf16 v[4:7], v[88:91], v[64:67], v[4:7]
	v_mfma_f32_16x16x32_bf16 v[0:3], v[92:95], v[64:67], v[0:3]
	s_setprio 0
	s_barrier
	s_cmpk_eq_i32 s10, 0x800
	s_cbranch_scc0 .LBB0_109
	s_branch .LBB0_113

; #define STAGE_ALL(bufi, kt) do { STAGEA(SA(bufi, 0), brow, kt); STAGEA(SA(bufi, 1), brow + HALF, kt); STAGEB(SB(bufi), bcol, kt); } while (0)
;     ...
;   const int wid = tid >> 6, lane = tid & 63, wr = wid >> 1, wc = wid & 1, fr = lane & 15, fq = lane >> 4;
;   acc_t acc;
; #pragma unroll
;   for (int m = 0; m < 4; ++m)
; #pragma unroll
;     for (int n = 0; n < 4; ++n) acc[m][n] = f32x4{0.f, 0.f, 0.f, 0.f};
;   const int nt = K / BK;
;   unsigned oA0, oA1, oB0, oB1;
;   { int _r, _c; stage_rc(tid * 16, _r, _c); oA0 = _r * lda + _c; oB0 = _r * ldb + _c;
;     stage_rc(tid * 16 + 8192, _r, _c); oA1 = _r * lda + _c; oB1 = _r * ldb + _c; }
;   if (!preloaded) {
;     STAGE_ALL(0, 0);
;     if (nt > 1) STAGE_ALL(1, 1);
;   }
.LBB0_1020:
	s_or_b64 exec, exec, s[10:11]
	v_lshlrev_b32_e32 v4, 13, v4
	s_ashr_i32 s41, s40, 31
	s_ashr_i32 s39, s38, 31
	v_and_b32_e32 v4, 0xffffc000, v4
	v_lshlrev_b32_e32 v0, 13, v0
	v_and_b32_e32 v8, 15, v133
	v_and_b32_e32 v9, 48, v133
	s_lshl_b64 s[10:11], s[40:41], 11
	s_lshl_b64 s[36:37], s[38:39], 11
	v_lshl_add_u32 v4, v5, 10, v4
	v_and_b32_e32 v0, 0xffffc000, v0
	v_lshl_or_b32 v8, v8, 6, v9
	v_lshlrev_b32_e32 v9, 2, v133
	v_or_b32_e32 v4, v4, v6
	s_add_u32 s36, s50, s36
	v_lshl_add_u32 v0, v1, 10, v0
	v_and_b32_e32 v9, 32, v9
	v_add_u32_sdwa v196, v4, sext(v7) dst_sel:DWORD dst_unused:UNUSED_PAD src0_sel:DWORD src1_sel:WORD_0
	s_addc_u32 s37, s51, s37
	v_or_b32_e32 v0, v0, v2
	v_xad_u32 v8, v8, v9, 16
	v_lshlrev_b32_e32 v9, 6, v133
	v_lshlrev_b32_e32 v10, 7, v133
	v_lshlrev_b64 v[4:5], 1, v[196:197]
	v_add_u32_sdwa v196, v0, sext(v3) dst_sel:DWORD dst_unused:UNUSED_PAD src0_sel:DWORD src1_sel:WORD_0
	s_add_u32 s10, s54, s10
	v_and_b32_e32 v9, 0x2000, v9
	v_and_b32_e32 v10, 0x2000, v10
	v_lshlrev_b64 v[0:1], 1, v[196:197]
	s_addc_u32 s11, s55, s11
	v_mov_b32_e32 v56, 0
	v_ashrrev_i32_e32 v132, 8, v133
	v_add_u32_e32 v129, v8, v9
	v_add_u32_e32 v131, v8, v10
	v_lshl_add_u64 v[134:135], s[36:37], 0, v[4:5]
	v_lshl_add_u64 v[136:137], s[36:37], 0, v[0:1]
	v_lshl_add_u64 v[138:139], s[10:11], 0, v[4:5]
	v_lshl_add_u64 v[140:141], s[10:11], 0, v[0:1]
	s_mov_b32 s39, 0
	s_mov_b64 s[10:11], 0
	s_mov_b32 s41, 0
	v_mov_b32_e32 v57, v56
	v_mov_b32_e32 v58, v56
	v_mov_b32_e32 v59, v56
	v_mov_b32_e32 v60, v56
	v_mov_b32_e32 v61, v56
	v_mov_b32_e32 v62, v56
	v_mov_b32_e32 v63, v56
	v_mov_b32_e32 v52, v56
	v_mov_b32_e32 v53, v56
	v_mov_b32_e32 v54, v56
	v_mov_b32_e32 v55, v56
	v_mov_b32_e32 v48, v56
	v_mov_b32_e32 v49, v56
	v_mov_b32_e32 v50, v56
	v_mov_b32_e32 v51, v56
	v_mov_b32_e32 v44, v56
	v_mov_b32_e32 v45, v56
	v_mov_b32_e32 v46, v56
	v_mov_b32_e32 v47, v56
	v_mov_b32_e32 v40, v56
	v_mov_b32_e32 v41, v56
	v_mov_b32_e32 v42, v56
	v_mov_b32_e32 v43, v56
	v_mov_b32_e32 v36, v56
	v_mov_b32_e32 v37, v56
	v_mov_b32_e32 v38, v56
	v_mov_b32_e32 v39, v56
	v_mov_b32_e32 v32, v56
	v_mov_b32_e32 v33, v56
	v_mov_b32_e32 v34, v56
	v_mov_b32_e32 v35, v56
	v_mov_b32_e32 v28, v56
	v_mov_b32_e32 v29, v56
	v_mov_b32_e32 v30, v56
	v_mov_b32_e32 v31, v56
	v_mov_b32_e32 v24, v56
	v_mov_b32_e32 v25, v56
	v_mov_b32_e32 v26, v56
	v_mov_b32_e32 v27, v56
	v_mov_b32_e32 v20, v56
	v_mov_b32_e32 v21, v56
	v_mov_b32_e32 v22, v56
	v_mov_b32_e32 v23, v56
	v_mov_b32_e32 v16, v56
	v_mov_b32_e32 v17, v56
	v_mov_b32_e32 v18, v56
	v_mov_b32_e32 v19, v56
	v_mov_b32_e32 v12, v56
	v_mov_b32_e32 v13, v56
	v_mov_b32_e32 v14, v56
	v_mov_b32_e32 v15, v56
	v_mov_b32_e32 v8, v56
	v_mov_b32_e32 v9, v56
	v_mov_b32_e32 v10, v56
	v_mov_b32_e32 v11, v56
	v_mov_b32_e32 v4, v56
	v_mov_b32_e32 v5, v56
	v_mov_b32_e32 v6, v56
	v_mov_b32_e32 v7, v56
	v_mov_b32_e32 v0, v56
	v_mov_b32_e32 v1, v56
	v_mov_b32_e32 v2, v56
	v_mov_b32_e32 v3, v56
	v_readfirstlane_b32 s99, v151
	v_lshl_add_u32 v174, v132, 14, v129
	v_mov_b32_e32 v161, v131
	v_lshl_add_u64 v[162:163], v[140:141], 0, s[20:21]
	v_lshl_add_u64 v[164:165], v[138:139], 0, s[20:21]
	v_lshl_add_u64 v[166:167], v[140:141], 0, s[22:23]
	v_lshl_add_u64 v[168:169], v[138:139], 0, s[22:23]
	v_mov_b64_e32 v[170:171], v[136:137]
	v_mov_b64_e32 v[172:173], v[134:135]
	v_mov_b32_e32 v160, v174
	s_add_u32 s98, s99, 0x18000
	s_mov_b64 vcc, 0

; #define STAGE_ALL(bufi, kt) do { STAGEA(SA(bufi, 0), brow, kt); STAGEA(SA(bufi, 1), brow + HALF, kt); STAGEB(SB(bufi), bcol, kt); } while (0)
; #define WAIT_V(n) asm volatile("s_waitcnt vmcnt(" #n ")" ::: "memory")
; #define BAR __builtin_amdgcn_s_barrier()
;     ...
;       if (t + 2 < nt) { const int b2 = (b == 0) ? 2 : b - 1; STAGE_ALL(b2, t + 2); WAIT_V(6); } else { WAIT_V(0); }
;       asm volatile("s_waitcnt lgkmcnt(0)" ::: "memory");
;       __builtin_amdgcn_sched_barrier(0);
;       BAR;
;       __builtin_amdgcn_sched_barrier(0);
;       __builtin_amdgcn_s_setprio(1);
; #pragma unroll
;       for (int k = 0; k < 2; ++k)
; #pragma unroll
;         for (int m = 0; m < 4; ++m)
; #pragma unroll
;           for (int n = 0; n < 4; ++n) acc[m][n] = __builtin_amdgcn_mfma_f32_16x16x32_bf16(Bf[n][k], At[m][k], acc[m][n], 0, 0, 0);
.LBB0_1021:
	s_waitcnt lgkmcnt(0)
	s_barrier
	s_setprio 1
	s_waitcnt lgkmcnt(0)
	v_mfma_f32_16x16x32_bf16 v[56:59], v[112:115], v[108:111], v[56:59]
	v_mfma_f32_16x16x32_bf16 v[60:63], v[116:119], v[108:111], v[60:63]
	s_cbranch_vccnz .Lgc4_skd3
	s_add_u32 m0, s98, 0x6000
	s_nop 0
	global_load_lds_dwordx4 v[168:169], off

; #define BAR __builtin_amdgcn_s_barrier()
;     ...
; #pragma unroll
;       for (int k = 0; k < 2; ++k)
; #pragma unroll
;         for (int m = 0; m < 4; ++m)
; #pragma unroll
;           for (int n = 0; n < 4; ++n) acc[m][n] = __builtin_amdgcn_mfma_f32_16x16x32_bf16(Bf[n][k], At[m][k], acc[m][n], 0, 0, 0);
;       __builtin_amdgcn_s_setprio(0);
;       __builtin_amdgcn_sched_barrier(0);
;       BAR;
;       __builtin_amdgcn_sched_barrier(0);
;       b = (b == 2) ? 0 : b + 1;
.Lgc4_skd5:
	v_mfma_f32_16x16x32_bf16 v[20:23], v[120:123], v[100:103], v[20:23]
	v_mfma_f32_16x16x32_bf16 v[16:19], v[124:127], v[100:103], v[16:19]
	v_mfma_f32_16x16x32_bf16 v[12:15], v[112:115], v[96:99], v[12:15]
	s_add_i32 s36, s39, 1
	s_cmp_lg_u32 s39, 2
	s_cselect_b32 s39, s36, 0
	s_add_i32 s41, s41, 1
	s_cmp_gt_u32 s41, 13
	s_cselect_b64 vcc, -1, 0
	s_add_u32 s10, s10, 0x80
	s_addc_u32 s11, s11, 0
	s_mul_i32 s36, s39, 0xc000
	s_mul_i32 s98, s39, 0x6000
	s_addk_i32 s98, 0xa000
	s_cmp_lg_u32 s39, 0
	s_cselect_b32 s98, s98, 0xc000
	s_lshl_b32 s98, s98, 1
	s_add_u32 s98, s98, s99
	v_mfma_f32_16x16x32_bf16 v[8:11], v[116:119], v[96:99], v[8:11]
	v_mfma_f32_16x16x32_bf16 v[4:7], v[120:123], v[96:99], v[4:7]
	v_add_u32_e32 v160, s36, v174
	v_mfma_f32_16x16x32_bf16 v[0:3], v[124:127], v[96:99], v[0:3]
	v_mfma_f32_16x16x32_bf16 v[56:59], v[80:83], v[76:79], v[56:59]
	v_add_u32_e32 v161, s36, v131
	v_mfma_f32_16x16x32_bf16 v[60:63], v[84:87], v[76:79], v[60:63]
	v_mfma_f32_16x16x32_bf16 v[52:55], v[88:91], v[76:79], v[52:55]
	v_lshl_add_u64 v[162:163], v[162:163], 0, s[14:15]
	v_mfma_f32_16x16x32_bf16 v[48:51], v[92:95], v[76:79], v[48:51]
	v_mfma_f32_16x16x32_bf16 v[44:47], v[80:83], v[72:75], v[44:47]
	v_lshl_add_u64 v[164:165], v[164:165], 0, s[14:15]
	v_mfma_f32_16x16x32_bf16 v[40:43], v[84:87], v[72:75], v[40:43]
	v_mfma_f32_16x16x32_bf16 v[36:39], v[88:91], v[72:75], v[36:39]
	v_lshl_add_u64 v[166:167], v[166:167], 0, s[14:15]
	v_mfma_f32_16x16x32_bf16 v[32:35], v[92:95], v[72:75], v[32:35]
	v_mfma_f32_16x16x32_bf16 v[28:31], v[80:83], v[68:71], v[28:31]
	v_lshl_add_u64 v[168:169], v[168:169], 0, s[14:15]
	v_mfma_f32_16x16x32_bf16 v[24:27], v[84:87], v[68:71], v[24:27]
	v_mfma_f32_16x16x32_bf16 v[20:23], v[88:91], v[68:71], v[20:23]
	v_lshl_add_u64 v[170:171], v[170:171], 0, s[14:15]
	v_mfma_f32_16x16x32_bf16 v[16:19], v[92:95], v[68:71], v[16:19]
	v_mfma_f32_16x16x32_bf16 v[12:15], v[80:83], v[64:67], v[12:15]
	v_lshl_add_u64 v[172:173], v[172:173], 0, s[14:15]
	v_mfma_f32_16x16x32_bf16 v[8:11], v[84:87], v[64:67], v[8:11]
	v_mfma_f32_16x16x32_bf16 v[4:7], v[88:91], v[64:67], v[4:7]
	v_mfma_f32_16x16x32_bf16 v[0:3], v[92:95], v[64:67], v[0:3]
	s_setprio 0
	s_barrier
	s_cmpk_eq_i32 s10, 0x800
	s_cbranch_scc0 .LBB0_1022
	s_branch .LBB0_1026

; #define STAGE_ALL(bufi, kt) do { STAGEA(SA(bufi, 0), brow, kt); STAGEA(SA(bufi, 1), brow + HALF, kt); STAGEB(SB(bufi), bcol, kt); } while (0)
;     ...
;   const int wid = tid >> 6, lane = tid & 63, wr = wid >> 1, wc = wid & 1, fr = lane & 15, fq = lane >> 4;
;   acc_t acc;
; #pragma unroll
;   for (int m = 0; m < 4; ++m)
; #pragma unroll
;     for (int n = 0; n < 4; ++n) acc[m][n] = f32x4{0.f, 0.f, 0.f, 0.f};
;   const int nt = K / BK;
;   unsigned oA0, oA1, oB0, oB1;
;   { int _r, _c; stage_rc(tid * 16, _r, _c); oA0 = _r * lda + _c; oB0 = _r * ldb + _c;
;     stage_rc(tid * 16 + 8192, _r, _c); oA1 = _r * lda + _c; oB1 = _r * ldb + _c; }
;   if (!preloaded) {
;     STAGE_ALL(0, 0);
;     if (nt > 1) STAGE_ALL(1, 1);
;   }
.LBB0_1056:
	s_or_b64 exec, exec, s[10:11]
	v_and_b32_e32 v8, 15, v133
	v_and_b32_e32 v9, 48, v133
	v_lshl_or_b32 v8, v8, 6, v9
	v_lshlrev_b32_e32 v9, 2, v133
	v_and_b32_e32 v9, 32, v9
	v_xad_u32 v8, v8, v9, 16
	v_lshlrev_b32_e32 v9, 6, v133
	v_lshlrev_b32_e32 v10, 7, v133
	v_and_b32_e32 v9, 0x2000, v9
	v_and_b32_e32 v10, 0x2000, v10
	s_movk_i32 s60, 0xb00
	v_add_u32_e32 v129, v8, v9
	v_add_u32_e32 v131, v8, v10
	v_lshrrev_b32_e32 v8, 1, v4
	v_mul_lo_u32 v4, v6, s60
	s_mov_b32 s61, 0xb000
	v_mad_u64_u32 v[8:9], s[10:11], v8, s61, v[4:5]
	v_or_b32_e32 v4, v8, v5
	s_add_u32 s10, s46, s41
	v_lshrrev_b32_e32 v6, 1, v0
	v_mul_lo_u32 v0, v2, s60
	v_add_u32_sdwa v196, v4, sext(v7) dst_sel:DWORD dst_unused:UNUSED_PAD src0_sel:DWORD src1_sel:WORD_0
	s_addc_u32 s11, s47, s40
	v_mad_u64_u32 v[6:7], s[40:41], v6, s61, v[0:1]
	v_or_b32_e32 v0, v6, v1
	v_lshlrev_b64 v[4:5], 1, v[196:197]
	v_add_u32_sdwa v196, v0, sext(v3) dst_sel:DWORD dst_unused:UNUSED_PAD src0_sel:DWORD src1_sel:WORD_0
	v_lshlrev_b64 v[0:1], 1, v[196:197]
	v_lshl_add_u64 v[134:135], s[10:11], 0, v[4:5]
	v_lshl_add_u64 v[136:137], s[10:11], 0, v[0:1]
	s_add_u32 s10, s54, s37
	s_addc_u32 s11, s55, s36
	v_mov_b32_e32 v60, 0
	v_ashrrev_i32_e32 v132, 8, v133
	v_lshl_add_u64 v[138:139], s[10:11], 0, v[4:5]
	v_lshl_add_u64 v[140:141], s[10:11], 0, v[0:1]
	s_mov_b32 s60, 0
	s_mov_b64 s[10:11], 0
	s_mov_b32 s61, 0
	v_mov_b32_e32 v61, v60
	v_mov_b32_e32 v62, v60
	v_mov_b32_e32 v63, v60
	v_mov_b32_e32 v56, v60
	v_mov_b32_e32 v57, v60
	v_mov_b32_e32 v58, v60
	v_mov_b32_e32 v59, v60
	v_mov_b32_e32 v52, v60
	v_mov_b32_e32 v53, v60
	v_mov_b32_e32 v54, v60
	v_mov_b32_e32 v55, v60
	v_mov_b32_e32 v48, v60
	v_mov_b32_e32 v49, v60
	v_mov_b32_e32 v50, v60
	v_mov_b32_e32 v51, v60
	v_mov_b32_e32 v44, v60
	v_mov_b32_e32 v45, v60
	v_mov_b32_e32 v46, v60
	v_mov_b32_e32 v47, v60
	v_mov_b32_e32 v40, v60
	v_mov_b32_e32 v41, v60
	v_mov_b32_e32 v42, v60
	v_mov_b32_e32 v43, v60
	v_mov_b32_e32 v36, v60
	v_mov_b32_e32 v37, v60
	v_mov_b32_e32 v38, v60
	v_mov_b32_e32 v39, v60
	v_mov_b32_e32 v32, v60
	v_mov_b32_e32 v33, v60
	v_mov_b32_e32 v34, v60
	v_mov_b32_e32 v35, v60
	v_mov_b32_e32 v28, v60
	v_mov_b32_e32 v29, v60
	v_mov_b32_e32 v30, v60
	v_mov_b32_e32 v31, v60
	v_mov_b32_e32 v24, v60
	v_mov_b32_e32 v25, v60
	v_mov_b32_e32 v26, v60
	v_mov_b32_e32 v27, v60
	v_mov_b32_e32 v20, v60
	v_mov_b32_e32 v21, v60
	v_mov_b32_e32 v22, v60
	v_mov_b32_e32 v23, v60
	v_mov_b32_e32 v16, v60
	v_mov_b32_e32 v17, v60
	v_mov_b32_e32 v18, v60
	v_mov_b32_e32 v19, v60
	v_mov_b32_e32 v12, v60
	v_mov_b32_e32 v13, v60
	v_mov_b32_e32 v14, v60
	v_mov_b32_e32 v15, v60
	v_mov_b32_e32 v8, v60
	v_mov_b32_e32 v9, v60
	v_mov_b32_e32 v10, v60
	v_mov_b32_e32 v11, v60
	v_mov_b32_e32 v4, v60
	v_mov_b32_e32 v5, v60
	v_mov_b32_e32 v6, v60
	v_mov_b32_e32 v7, v60
	v_mov_b32_e32 v0, v60
	v_mov_b32_e32 v1, v60
	v_mov_b32_e32 v2, v60
	v_mov_b32_e32 v3, v60
	v_readfirstlane_b32 s99, v151
	v_lshl_add_u32 v174, v132, 14, v129
	v_mov_b32_e32 v161, v131
	v_lshl_add_u64 v[162:163], v[140:141], 0, s[16:17]
	v_lshl_add_u64 v[164:165], v[138:139], 0, s[16:17]
	v_lshl_add_u64 v[166:167], v[140:141], 0, s[18:19]
	v_lshl_add_u64 v[168:169], v[138:139], 0, s[18:19]
	v_mov_b64_e32 v[170:171], v[136:137]
	v_mov_b64_e32 v[172:173], v[134:135]
	v_mov_b32_e32 v160, v174
	s_add_u32 s98, s99, 0x18000
	s_mov_b64 vcc, 0

; #define BAR __builtin_amdgcn_s_barrier()
;     ...
; #pragma unroll
;       for (int k = 0; k < 2; ++k)
; #pragma unroll
;         for (int m = 0; m < 4; ++m)
; #pragma unroll
;           for (int n = 0; n < 4; ++n) acc[m][n] = __builtin_amdgcn_mfma_f32_16x16x32_bf16(Bf[n][k], At[m][k], acc[m][n], 0, 0, 0);
;       __builtin_amdgcn_s_setprio(0);
;       __builtin_amdgcn_sched_barrier(0);
;       BAR;
;       __builtin_amdgcn_sched_barrier(0);
;       b = (b == 2) ? 0 : b + 1;
.Lgc5_skd5:
	v_mfma_f32_16x16x32_bf16 v[20:23], v[120:123], v[100:103], v[20:23]
	v_mfma_f32_16x16x32_bf16 v[16:19], v[124:127], v[100:103], v[16:19]
	v_mfma_f32_16x16x32_bf16 v[12:15], v[112:115], v[96:99], v[12:15]
	s_add_i32 s36, s60, 1
	s_cmp_lg_u32 s60, 2
	s_cselect_b32 s60, s36, 0
	s_add_i32 s61, s61, 1
	s_cmp_gt_u32 s61, 41
	s_cselect_b64 vcc, -1, 0
	s_add_u32 s10, s10, 0x80
	s_addc_u32 s11, s11, 0
	s_mul_i32 s36, s60, 0xc000
	s_mul_i32 s98, s60, 0x6000
	s_addk_i32 s98, 0xa000
	s_cmp_lg_u32 s60, 0
	s_cselect_b32 s98, s98, 0xc000
	s_lshl_b32 s98, s98, 1
	s_add_u32 s98, s98, s99
	v_mfma_f32_16x16x32_bf16 v[8:11], v[116:119], v[96:99], v[8:11]
	v_mfma_f32_16x16x32_bf16 v[4:7], v[120:123], v[96:99], v[4:7]
	v_add_u32_e32 v160, s36, v174
	v_mfma_f32_16x16x32_bf16 v[0:3], v[124:127], v[96:99], v[0:3]
	v_mfma_f32_16x16x32_bf16 v[60:63], v[80:83], v[76:79], v[60:63]
	v_add_u32_e32 v161, s36, v131
	v_mfma_f32_16x16x32_bf16 v[56:59], v[84:87], v[76:79], v[56:59]
	v_mfma_f32_16x16x32_bf16 v[52:55], v[88:91], v[76:79], v[52:55]
	v_lshl_add_u64 v[162:163], v[162:163], 0, s[14:15]
	v_mfma_f32_16x16x32_bf16 v[48:51], v[92:95], v[76:79], v[48:51]
	v_mfma_f32_16x16x32_bf16 v[44:47], v[80:83], v[72:75], v[44:47]
	v_lshl_add_u64 v[164:165], v[164:165], 0, s[14:15]
	v_mfma_f32_16x16x32_bf16 v[40:43], v[84:87], v[72:75], v[40:43]
	v_mfma_f32_16x16x32_bf16 v[36:39], v[88:91], v[72:75], v[36:39]
	v_lshl_add_u64 v[166:167], v[166:167], 0, s[14:15]
	v_mfma_f32_16x16x32_bf16 v[32:35], v[92:95], v[72:75], v[32:35]
	v_mfma_f32_16x16x32_bf16 v[28:31], v[80:83], v[68:71], v[28:31]
	v_lshl_add_u64 v[168:169], v[168:169], 0, s[14:15]
	v_mfma_f32_16x16x32_bf16 v[24:27], v[84:87], v[68:71], v[24:27]
	v_mfma_f32_16x16x32_bf16 v[20:23], v[88:91], v[68:71], v[20:23]
	v_lshl_add_u64 v[170:171], v[170:171], 0, s[14:15]
	v_mfma_f32_16x16x32_bf16 v[16:19], v[92:95], v[68:71], v[16:19]
	v_mfma_f32_16x16x32_bf16 v[12:15], v[80:83], v[64:67], v[12:15]
	v_lshl_add_u64 v[172:173], v[172:173], 0, s[14:15]
	v_mfma_f32_16x16x32_bf16 v[8:11], v[84:87], v[64:67], v[8:11]
	v_mfma_f32_16x16x32_bf16 v[4:7], v[88:91], v[64:67], v[4:7]
	v_mfma_f32_16x16x32_bf16 v[0:3], v[92:95], v[64:67], v[0:3]
	s_setprio 0
	s_barrier
	s_cmpk_eq_i32 s10, 0x1600
	s_cbranch_scc0 .LBB0_1058
	s_branch .LBB0_1062

; #define STAGE_ALL(bufi, kt) do { STAGEA(SA(bufi, 0), brow, kt); STAGEA(SA(bufi, 1), brow + HALF, kt); STAGEB(SB(bufi), bcol, kt); } while (0)
;     ...
;   const int wid = tid >> 6, lane = tid & 63, wr = wid >> 1, wc = wid & 1, fr = lane & 15, fq = lane >> 4;
;   acc_t acc;
; #pragma unroll
;   for (int m = 0; m < 4; ++m)
; #pragma unroll
;     for (int n = 0; n < 4; ++n) acc[m][n] = f32x4{0.f, 0.f, 0.f, 0.f};
;   const int nt = K / BK;
;   unsigned oA0, oA1, oB0, oB1;
;   { int _r, _c; stage_rc(tid * 16, _r, _c); oA0 = _r * lda + _c; oB0 = _r * ldb + _c;
;     stage_rc(tid * 16 + 8192, _r, _c); oA1 = _r * lda + _c; oB1 = _r * ldb + _c; }
;   if (!preloaded) {
;     STAGE_ALL(0, 0);
;     if (nt > 1) STAGE_ALL(1, 1);
;   }
.LBB0_1264:
	s_or_b64 exec, exec, s[44:45]
	v_lshlrev_b32_e32 v4, 13, v4
	v_and_b32_e32 v4, 0xffffc000, v4
	v_lshlrev_b32_e32 v0, 13, v0
	v_lshl_add_u32 v4, v5, 10, v4
	v_and_b32_e32 v0, 0xffffc000, v0
	s_ashr_i32 s43, s42, 31
	s_ashr_i32 s11, s10, 31
	v_or_b32_e32 v4, v4, v6
	v_lshl_add_u32 v0, v1, 10, v0
	v_and_b32_e32 v8, 15, v141
	v_and_b32_e32 v9, 48, v141
	s_lshl_b64 s[36:37], s[42:43], 11
	s_lshl_b64 s[10:11], s[10:11], 11
	v_add_u32_sdwa v196, v4, sext(v7) dst_sel:DWORD dst_unused:UNUSED_PAD src0_sel:DWORD src1_sel:WORD_0
	v_or_b32_e32 v0, v0, v2
	v_lshl_or_b32 v8, v8, 6, v9
	v_lshlrev_b32_e32 v9, 2, v141
	v_lshlrev_b64 v[4:5], 1, v[196:197]
	s_add_u32 s10, s48, s10
	v_add_u32_sdwa v196, v0, sext(v3) dst_sel:DWORD dst_unused:UNUSED_PAD src0_sel:DWORD src1_sel:WORD_0
	v_and_b32_e32 v9, 32, v9
	s_addc_u32 s11, s49, s11
	v_lshlrev_b64 v[0:1], 1, v[196:197]
	v_xad_u32 v8, v8, v9, 16
	v_lshlrev_b32_e32 v9, 6, v141
	v_lshlrev_b32_e32 v10, 7, v141
	v_lshl_add_u64 v[132:133], s[10:11], 0, v[4:5]
	v_lshl_add_u64 v[134:135], s[10:11], 0, v[0:1]
	s_add_u32 s10, s54, s36
	v_and_b32_e32 v9, 0x2000, v9
	v_and_b32_e32 v10, 0x2000, v10
	s_addc_u32 s11, s55, s37
	v_mov_b32_e32 v56, 0
	v_add_u32_e32 v129, v8, v9
	v_add_u32_e32 v131, v8, v10
	v_lshl_add_u64 v[136:137], s[10:11], 0, v[4:5]
	v_lshl_add_u64 v[138:139], s[10:11], 0, v[0:1]
	s_mov_b32 s43, 0
	s_mov_b64 s[10:11], 0
	s_mov_b32 s58, 0
	v_mov_b32_e32 v57, v56
	v_mov_b32_e32 v58, v56
	v_mov_b32_e32 v59, v56
	v_mov_b32_e32 v48, v56
	v_mov_b32_e32 v49, v56
	v_mov_b32_e32 v50, v56
	v_mov_b32_e32 v51, v56
	v_mov_b32_e32 v60, v56
	v_mov_b32_e32 v61, v56
	v_mov_b32_e32 v62, v56
	v_mov_b32_e32 v63, v56
	v_mov_b32_e32 v52, v56
	v_mov_b32_e32 v53, v56
	v_mov_b32_e32 v54, v56
	v_mov_b32_e32 v55, v56
	v_mov_b32_e32 v40, v56
	v_mov_b32_e32 v41, v56
	v_mov_b32_e32 v42, v56
	v_mov_b32_e32 v43, v56
	v_mov_b32_e32 v32, v56
	v_mov_b32_e32 v33, v56
	v_mov_b32_e32 v34, v56
	v_mov_b32_e32 v35, v56
	v_mov_b32_e32 v44, v56
	v_mov_b32_e32 v45, v56
	v_mov_b32_e32 v46, v56
	v_mov_b32_e32 v47, v56
	v_mov_b32_e32 v36, v56
	v_mov_b32_e32 v37, v56
	v_mov_b32_e32 v38, v56
	v_mov_b32_e32 v39, v56
	v_mov_b32_e32 v24, v56
	v_mov_b32_e32 v25, v56
	v_mov_b32_e32 v26, v56
	v_mov_b32_e32 v27, v56
	v_mov_b32_e32 v16, v56
	v_mov_b32_e32 v17, v56
	v_mov_b32_e32 v18, v56
	v_mov_b32_e32 v19, v56
	v_mov_b32_e32 v28, v56
	v_mov_b32_e32 v29, v56
	v_mov_b32_e32 v30, v56
	v_mov_b32_e32 v31, v56
	v_mov_b32_e32 v20, v56
	v_mov_b32_e32 v21, v56
	v_mov_b32_e32 v22, v56
	v_mov_b32_e32 v23, v56
	v_mov_b32_e32 v8, v56
	v_mov_b32_e32 v9, v56
	v_mov_b32_e32 v10, v56
	v_mov_b32_e32 v11, v56
	v_mov_b32_e32 v0, v56
	v_mov_b32_e32 v1, v56
	v_mov_b32_e32 v2, v56
	v_mov_b32_e32 v3, v56
	v_mov_b32_e32 v12, v56
	v_mov_b32_e32 v13, v56
	v_mov_b32_e32 v14, v56
	v_mov_b32_e32 v15, v56
	v_mov_b32_e32 v4, v56
	v_mov_b32_e32 v5, v56
	v_mov_b32_e32 v6, v56
	v_mov_b32_e32 v7, v56
	v_ashrrev_i32_e32 v140, 8, v141
	v_readfirstlane_b32 s99, v151
	v_lshl_add_u32 v174, v140, 14, v129
	v_mov_b32_e32 v161, v131
	v_lshl_add_u64 v[162:163], v[138:139], 0, s[20:21]
	v_lshl_add_u64 v[164:165], v[136:137], 0, s[20:21]
	v_lshl_add_u64 v[166:167], v[138:139], 0, s[22:23]
	v_lshl_add_u64 v[168:169], v[136:137], 0, s[22:23]
	v_mov_b64_e32 v[170:171], v[134:135]
	v_mov_b64_e32 v[172:173], v[132:133]
	v_mov_b32_e32 v160, v174
	s_add_u32 s98, s99, 0x18000
	s_mov_b64 vcc, 0

; #define BAR __builtin_amdgcn_s_barrier()
;     ...
; #pragma unroll
;       for (int k = 0; k < 2; ++k)
; #pragma unroll
;         for (int m = 0; m < 4; ++m)
; #pragma unroll
;           for (int n = 0; n < 4; ++n) acc[m][n] = __builtin_amdgcn_mfma_f32_16x16x32_bf16(Bf[n][k], At[m][k], acc[m][n], 0, 0, 0);
;       __builtin_amdgcn_s_setprio(0);
;       __builtin_amdgcn_sched_barrier(0);
;       BAR;
;       __builtin_amdgcn_sched_barrier(0);
;       b = (b == 2) ? 0 : b + 1;
.Lgc6_skd5:
	v_mfma_f32_16x16x32_bf16 v[28:31], v[120:123], v[100:103], v[28:31]
	v_mfma_f32_16x16x32_bf16 v[20:23], v[124:127], v[100:103], v[20:23]
	v_mfma_f32_16x16x32_bf16 v[8:11], v[112:115], v[96:99], v[8:11]
	s_add_i32 s36, s43, 1
	s_cmp_lg_u32 s43, 2
	s_cselect_b32 s43, s36, 0
	s_add_i32 s58, s58, 1
	s_cmp_gt_u32 s58, 13
	s_cselect_b64 vcc, -1, 0
	s_add_u32 s10, s10, 0x80
	s_addc_u32 s11, s11, 0
	s_mul_i32 s36, s43, 0xc000
	s_mul_i32 s98, s43, 0x6000
	s_addk_i32 s98, 0xa000
	s_cmp_lg_u32 s43, 0
	s_cselect_b32 s98, s98, 0xc000
	s_lshl_b32 s98, s98, 1
	s_add_u32 s98, s98, s99
	v_mfma_f32_16x16x32_bf16 v[0:3], v[116:119], v[96:99], v[0:3]
	v_mfma_f32_16x16x32_bf16 v[12:15], v[120:123], v[96:99], v[12:15]
	v_add_u32_e32 v160, s36, v174
	v_mfma_f32_16x16x32_bf16 v[4:7], v[124:127], v[96:99], v[4:7]
	v_mfma_f32_16x16x32_bf16 v[56:59], v[80:83], v[76:79], v[56:59]
	v_add_u32_e32 v161, s36, v131
	v_mfma_f32_16x16x32_bf16 v[48:51], v[84:87], v[76:79], v[48:51]
	v_mfma_f32_16x16x32_bf16 v[60:63], v[88:91], v[76:79], v[60:63]
	v_lshl_add_u64 v[162:163], v[162:163], 0, s[14:15]
	v_mfma_f32_16x16x32_bf16 v[52:55], v[92:95], v[76:79], v[52:55]
	v_mfma_f32_16x16x32_bf16 v[40:43], v[80:83], v[72:75], v[40:43]
	v_lshl_add_u64 v[164:165], v[164:165], 0, s[14:15]
	v_mfma_f32_16x16x32_bf16 v[32:35], v[84:87], v[72:75], v[32:35]
	v_mfma_f32_16x16x32_bf16 v[44:47], v[88:91], v[72:75], v[44:47]
	v_lshl_add_u64 v[166:167], v[166:167], 0, s[14:15]
	v_mfma_f32_16x16x32_bf16 v[36:39], v[92:95], v[72:75], v[36:39]
	v_mfma_f32_16x16x32_bf16 v[24:27], v[80:83], v[68:71], v[24:27]
	v_lshl_add_u64 v[168:169], v[168:169], 0, s[14:15]
	v_mfma_f32_16x16x32_bf16 v[16:19], v[84:87], v[68:71], v[16:19]
	v_mfma_f32_16x16x32_bf16 v[28:31], v[88:91], v[68:71], v[28:31]
	v_lshl_add_u64 v[170:171], v[170:171], 0, s[14:15]
	v_mfma_f32_16x16x32_bf16 v[20:23], v[92:95], v[68:71], v[20:23]
	v_mfma_f32_16x16x32_bf16 v[8:11], v[80:83], v[64:67], v[8:11]
	v_lshl_add_u64 v[172:173], v[172:173], 0, s[14:15]
	v_mfma_f32_16x16x32_bf16 v[0:3], v[84:87], v[64:67], v[0:3]
	v_mfma_f32_16x16x32_bf16 v[12:15], v[88:91], v[64:67], v[12:15]
	v_mfma_f32_16x16x32_bf16 v[4:7], v[92:95], v[64:67], v[4:7]
	s_setprio 0
	s_barrier
	s_cmpk_eq_i32 s10, 0x800
	s_cbranch_scc0 .LBB0_1266
	s_branch .LBB0_1270
